# attention tile loop: the first sub-tile's four early Q fragment reads are requested in front of the tile barrier (previous tile's last MFMAs / staging / prologue), halving the LDS read burst after the
# speedup vs baseline: 1.0018x; 1.0018x over previous
; #define LAS __attribute__((address_space(3)))
; __device__ __forceinline__ void dattn_unit(LAS unsigned char* lds, int b, int h, int qb, const bf16* Q, const bf16* K, const bf16* V, bf16* YB, float lam, const float* subg, float oml, int tid) {
;     ...
;     const int lane = tid & 63, w = __builtin_amdgcn_readfirstlane(tid >> 6), ql = lane & 31, hi = lane >> 5;
;     const LAS float* tab = (const LAS float*)(lds + AT_TAB);
;     const size_t rowb = (size_t)b * SEQ;
;     const int qmin = qb * 256 + w * 32, q = qmin + ql, qmax = qmin + 31;
;     LAS bf16x8* qs = (LAS bf16x8*)(lds + AT_QS) + w * 512 + lane;
; #pragma unroll
;     for (int mp = 0; mp < 2; ++mp)
; #pragma unroll
;         for (int ks = 0; ks < 4; ++ks) qs[(mp * 4 + ks) * 64] = *(const bf16x8*)(Q + (rowb + q) * 1024 + h * 128 + mp * 64 + ks * 16 + hi * 8);
;     f32x16 o[2][4];
; #pragma unroll
;     for (int mp = 0; mp < 2; ++mp)
; #pragma unroll
;         for (int cb = 0; cb < 4; ++cb) o[mp][cb] = f32x16{};
;     float mref[2] = {0.f, 0.f}, lsum[2] = {0.f, 0.f};
;     const int NT = 4 * qb + 4;
;     const bf16* kg = K + (rowb + (tid >> 3)) * 1024 + h * 128 + (tid & 7) * 8;
;     const bf16* vg = V + (rowb + (tid & 63)) * 1024 + h * 128 + (tid >> 6) * 16;
;     v4u kr0 = *(const v4u*)(kg), kr1 = *(const v4u*)(kg + 64), vr0 = *(const v4u*)(vg), vr1 = *(const v4u*)(vg + 8);
;     ...
;     AT_STAGE(0);
;     __syncthreads();
.LBB0_225:
	v_mov_b32_e32 v54, v211
	s_lshl_b32 s19, s35, 8
	v_ashrrev_i32_e32 v52, 6, v54
	v_ashrrev_i32_e32 v48, 3, v54
	v_readfirstlane_b32 s18, v52
	s_lshl_b32 s31, s18, 5
	v_ashrrev_i32_e32 v49, 31, v48
	v_and_b32_e32 v55, 31, v54
	s_add_i32 s31, s31, s19
	v_lshl_add_u64 v[32:33], s[6:7], 0, v[48:49]
	v_lshlrev_b32_e32 v34, 3, v54
	v_or_b32_e32 v178, s31, v55
	v_lshlrev_b64 v[32:33], 11, v[32:33]
	v_and_b32_e32 v34, 56, v34
	v_and_b32_e32 v53, 63, v54
	v_ashrrev_i32_e32 v179, 31, v178
	v_lshl_add_u64 v[32:33], s[10:11], 0, v[32:33]
	v_lshlrev_b32_e32 v180, 1, v34
	v_mov_b32_e32 v181, v209
	v_lshl_add_u64 v[0:1], s[6:7], 0, v[178:179]
	v_lshl_add_u64 v[36:37], v[32:33], 0, v[180:181]
	v_or_b32_e32 v32, s6, v53
	v_mov_b32_e32 v33, s7
	v_lshlrev_b32_e32 v34, 4, v52
	v_bfe_u32 v194, v54, 5, 1
	v_lshlrev_b64 v[0:1], 11, v[0:1]
	v_lshlrev_b64 v[32:33], 11, v[32:33]
	v_ashrrev_i32_e32 v35, 31, v34
	v_lshl_add_u64 v[176:177], s[8:9], 0, v[0:1]
	v_lshlrev_b32_e32 v208, 4, v194
	v_lshl_add_u64 v[32:33], s[20:21], 0, v[32:33]
	v_lshlrev_b64 v[50:51], 1, v[34:35]
	v_lshl_add_u64 v[28:29], v[176:177], 0, v[208:209]
	v_lshl_add_u64 v[44:45], v[32:33], 0, v[50:51]
	global_load_dwordx4 v[0:3], v[28:29], off
	global_load_dwordx4 v[4:7], v[28:29], off offset:32
	global_load_dwordx4 v[8:11], v[28:29], off offset:64
	global_load_dwordx4 v[12:15], v[28:29], off offset:96
	global_load_dwordx4 v[16:19], v[28:29], off offset:128
	global_load_dwordx4 v[20:23], v[28:29], off offset:160
	global_load_dwordx4 v[24:27], v[28:29], off offset:192
	s_nop 0
	global_load_dwordx4 v[28:31], v[28:29], off offset:224
	s_nop 0
	global_load_dwordx4 v[32:35], v[36:37], off
	s_nop 0
	global_load_dwordx4 v[36:39], v[36:37], off offset:128
	s_nop 0
	global_load_dwordx4 v[40:43], v[44:45], off
	s_nop 0
	global_load_dwordx4 v[44:47], v[44:45], off offset:16
	s_lshl_b32 s19, s35, 10
	s_or_b32 s56, s19, 0x300
	s_movk_i32 s19, 0x48
	s_lshl_b32 s18, s18, 13
	v_mul_lo_u32 v56, v48, s19
	s_movk_i32 s19, 0x480
	s_add_i32 s18, s18, 0
	v_mul_lo_u32 v57, v52, s19
	v_lshlrev_b32_e32 v195, 1, v53
	v_lshrrev_b32_e32 v58, 2, v53
	v_lshrrev_b32_e32 v59, 3, v53
	v_xor_b32_e32 v58, v58, v59
	v_and_b32_e32 v58, 1, v58
	v_mul_u32_u24_e32 v58, 24, v58
	v_xor_b32_e32 v195, v195, v58
	v_lshlrev_b32_e32 v52, 11, v53
	v_lshl_add_u32 v53, v53, 4, s18
	v_lshlrev_b32_e32 v196, 1, v56
	v_lshlrev_b32_e32 v197, 1, v57
	v_add_u32_e32 v189, 0x12400, v53
	v_mov_b32_e32 v53, v209
	v_mul_u32_u24_e32 v192, 0x90, v55
	v_add3_u32 v55, 0, v196, v180
	v_add3_u32 v56, 0, v197, v195
	v_lshlrev_b32_e32 v193, 4, v194
	s_or_b32 s35, s31, 31
	s_mov_b32 s57, 0
	v_mov_b32_e32 v179, 0
	s_movk_i32 s58, 0xb0
	v_mov_b32_e32 v181, 0
	v_mov_b32_e32 v190, 0
	v_mov_b32_e32 v191, 0
	s_mov_b32 s59, 0
	s_waitcnt vmcnt(11)
	ds_write_b128 v189, v[0:3]
	s_waitcnt vmcnt(10)
	ds_write_b128 v189, v[4:7] offset:1024
	s_waitcnt vmcnt(9)
	ds_write_b128 v189, v[8:11] offset:2048
	s_waitcnt vmcnt(8)
	ds_write_b128 v189, v[12:15] offset:3072
	s_waitcnt vmcnt(7)
	ds_write_b128 v189, v[16:19] offset:4096
	s_waitcnt vmcnt(6)
	ds_write_b128 v189, v[20:23] offset:5120
	s_waitcnt vmcnt(5)
	ds_write_b128 v189, v[24:27] offset:6144
	s_waitcnt vmcnt(4)
	ds_write_b128 v189, v[28:31] offset:7168
	s_waitcnt vmcnt(3)
	ds_write_b128 v55, v[32:35]
	s_waitcnt vmcnt(2)
	ds_write_b128 v55, v[36:39] offset:9216
	s_waitcnt vmcnt(1)
	ds_write_b16 v56, v40 offset:18432
	ds_write_b16_d16_hi v56, v40 offset:18576
	ds_write_b16 v56, v41 offset:18720
	ds_write_b16_d16_hi v56, v41 offset:18864
	ds_write_b16 v56, v42 offset:19008
	ds_write_b16_d16_hi v56, v42 offset:19152
	ds_write_b16 v56, v43 offset:19296
	ds_write_b16_d16_hi v56, v43 offset:19440
	s_waitcnt vmcnt(0)
	ds_write_b16 v56, v44 offset:19584
	ds_write_b16_d16_hi v56, v44 offset:19728
	ds_write_b16 v56, v45 offset:19872
	ds_write_b16_d16_hi v56, v45 offset:20016
	ds_write_b16 v56, v46 offset:20160
	ds_write_b16_d16_hi v56, v46 offset:20304
	ds_write_b16 v56, v47 offset:20448
	ds_write_b16_d16_hi v56, v47 offset:20592
	v_lshl_add_u64 v[0:1], v[52:53], 0, v[50:51]
	v_lshl_add_u64 v[182:183], s[44:45], 0, v[0:1]
	v_lshlrev_b64 v[0:1], 11, v[48:49]
	v_and_b32_e32 v2, 7, v54
	v_lshl_or_b32 v0, v2, 4, v0
	v_lshl_add_u64 v[184:185], s[44:45], 0, v[0:1]
	v_lshlrev_b32_e32 v0, 2, v178
	v_sub_u32_e32 v0, v208, v0
	v_mov_b32_e32 v14, v209
	v_mov_b32_e32 v15, v209
	v_add_u32_e32 v198, 0, v0
	v_mov_b32_e32 v0, v209
	v_mov_b32_e32 v1, v209
	v_mov_b32_e32 v2, v209
	v_mov_b32_e32 v3, v209
	v_mov_b32_e32 v4, v209
	v_mov_b32_e32 v5, v209
	v_mov_b32_e32 v6, v209
	v_mov_b32_e32 v7, v209
	v_mov_b32_e32 v8, v209
	v_mov_b32_e32 v9, v209
	v_mov_b32_e32 v10, v209
	v_mov_b32_e32 v11, v209
	v_mov_b32_e32 v12, v209
	v_mov_b32_e32 v13, v209
	v_mov_b64_e32 v[46:47], v[14:15]
	v_mov_b64_e32 v[78:79], v[14:15]
	v_mov_b64_e32 v[110:111], v[14:15]
	v_mov_b64_e32 v[30:31], v[14:15]
	v_mov_b64_e32 v[62:63], v[14:15]
	v_mov_b64_e32 v[94:95], v[14:15]
	v_mov_b64_e32 v[126:127], v[14:15]
	v_mov_b64_e32 v[44:45], v[12:13]
	v_mov_b64_e32 v[42:43], v[10:11]
	v_mov_b64_e32 v[40:41], v[8:9]
	v_mov_b64_e32 v[38:39], v[6:7]
	v_mov_b64_e32 v[36:37], v[4:5]
	v_mov_b64_e32 v[34:35], v[2:3]
	v_mov_b64_e32 v[32:33], v[0:1]
	v_mov_b64_e32 v[76:77], v[12:13]
	v_mov_b64_e32 v[74:75], v[10:11]
	v_mov_b64_e32 v[72:73], v[8:9]
	v_mov_b64_e32 v[70:71], v[6:7]
	v_mov_b64_e32 v[68:69], v[4:5]
	v_mov_b64_e32 v[66:67], v[2:3]
	v_mov_b64_e32 v[64:65], v[0:1]
	v_mov_b64_e32 v[108:109], v[12:13]
	v_mov_b64_e32 v[106:107], v[10:11]
	v_mov_b64_e32 v[104:105], v[8:9]
	v_mov_b64_e32 v[102:103], v[6:7]
	v_mov_b64_e32 v[100:101], v[4:5]
	v_mov_b64_e32 v[98:99], v[2:3]
	v_mov_b64_e32 v[96:97], v[0:1]
	v_mov_b64_e32 v[28:29], v[12:13]
	v_mov_b64_e32 v[26:27], v[10:11]
	v_mov_b64_e32 v[24:25], v[8:9]
	v_mov_b64_e32 v[22:23], v[6:7]
	v_mov_b64_e32 v[20:21], v[4:5]
	v_mov_b64_e32 v[18:19], v[2:3]
	v_mov_b64_e32 v[16:17], v[0:1]
	v_mov_b64_e32 v[60:61], v[12:13]
	v_mov_b64_e32 v[58:59], v[10:11]
	v_mov_b64_e32 v[56:57], v[8:9]
	v_mov_b64_e32 v[54:55], v[6:7]
	v_mov_b64_e32 v[52:53], v[4:5]
	v_mov_b64_e32 v[50:51], v[2:3]
	v_mov_b64_e32 v[48:49], v[0:1]
	v_mov_b64_e32 v[92:93], v[12:13]
	v_mov_b64_e32 v[90:91], v[10:11]
	v_mov_b64_e32 v[88:89], v[8:9]
	v_mov_b64_e32 v[86:87], v[6:7]
	v_mov_b64_e32 v[84:85], v[4:5]
	v_mov_b64_e32 v[82:83], v[2:3]
	v_mov_b64_e32 v[80:81], v[0:1]
	v_mov_b64_e32 v[124:125], v[12:13]
	v_mov_b64_e32 v[122:123], v[10:11]
	v_mov_b64_e32 v[120:121], v[8:9]
	v_mov_b64_e32 v[118:119], v[6:7]
	v_mov_b64_e32 v[116:117], v[4:5]
	v_mov_b64_e32 v[114:115], v[2:3]
	v_mov_b64_e32 v[112:113], v[0:1]
	s_add_u32 s98, s16, 0x1b020000
	s_addc_u32 s99, s17, 0
	s_add_u32 s100, s16, 0xb020000
	s_addc_u32 s101, s17, 0
	ds_read_b128 v[204:207], v189
	ds_read_b128 v[218:221], v189 offset:4096
	ds_read_b128 v[230:233], v189 offset:1024
	ds_read_b128 v[234:237], v189 offset:5120
	s_waitcnt lgkmcnt(0)
	s_barrier
	s_branch .LBB0_227

; __device__ __forceinline__ void dattn_unit(LAS unsigned char* lds, int b, int h, int qb, const bf16* Q, const bf16* K, const bf16* V, bf16* YB, float lam, const float* subg, float oml, int tid) {
;     ...
;         if (t + 1 < NT) AT_STAGE((t + 1) & 1);
;         __syncthreads();
.LBB0_226:
	s_add_i32 s59, s59, 1
	s_bitcmp1_b32 s59, 0
	s_cselect_b32 s18, 0x9000, 0
	s_add_i32 s60, s18, 0
	v_add3_u32 v128, s60, v196, v180
	s_addk_i32 s57, 0x100
	s_add_i32 s58, s58, 64
	s_waitcnt vmcnt(3)
	ds_write_b128 v128, v[168:171]
	s_waitcnt vmcnt(2)
	ds_write_b128 v128, v[172:175] offset:9216
	v_add3_u32 v128, s60, v197, v195
	s_add_u32 s98, s98, s14
	s_addc_u32 s99, s99, s15
	s_add_u32 s100, s100, s14
	s_addc_u32 s101, s101, s15
	s_cmp_lg_u32 s56, s57
	s_waitcnt vmcnt(1)
	ds_write_b16 v128, v164 offset:18432
	ds_write_b16_d16_hi v128, v164 offset:18576
	ds_write_b16 v128, v165 offset:18720
	ds_write_b16_d16_hi v128, v165 offset:18864
	ds_write_b16 v128, v166 offset:19008
	ds_write_b16_d16_hi v128, v166 offset:19152
	ds_write_b16 v128, v167 offset:19296
	ds_write_b16_d16_hi v128, v167 offset:19440
	s_waitcnt vmcnt(0)
	ds_write_b16 v128, v160 offset:19584
	ds_write_b16_d16_hi v128, v160 offset:19728
	ds_write_b16 v128, v161 offset:19872
	ds_write_b16_d16_hi v128, v161 offset:20016
	ds_write_b16 v128, v162 offset:20160
	ds_write_b16_d16_hi v128, v162 offset:20304
	ds_write_b16 v128, v163 offset:20448
	ds_write_b16_d16_hi v128, v163 offset:20592
	ds_read_b128 v[204:207], v189
	ds_read_b128 v[218:221], v189 offset:4096
	ds_read_b128 v[230:233], v189 offset:1024
	ds_read_b128 v[234:237], v189 offset:5120

; #define LAS __attribute__((address_space(3)))
; __device__ __forceinline__ void dattn_unit(LAS unsigned char* lds, int b, int h, int qb, const bf16* Q, const bf16* K, const bf16* V, bf16* YB, float lam, const float* subg, float oml, int tid) {
;     ...
;             if (kvbase + 32 * sub > qmax) continue;
;             const bool need_bm = kvbase + 32 * sub + 31 + 113 > qmin;
;             LAS bf16x8* qsp = qs; asm volatile("" : "+v"(qsp));
;             f32x16 s0, s1;
; #pragma unroll
;             for (int r = 0; r < 16; ++r) { s0[r] = -mref[0]; s1[r] = -mref[1]; }
;             {
;                 const LAS bf16* kp = Ks + (32 * sub + ql) * 72 + hi * 8;
;                 bf16x8 ka = *(const LAS bf16x8*)kp, kb = *(const LAS bf16x8*)(kp + 64 * 72), qa = qsp[0], qb = qsp[4 * 64];
;                 __builtin_amdgcn_sched_group_barrier(0x100, 4, 0);
; #pragma unroll
;                 for (int ks = 0; ks < 4; ++ks) { bf16x8 ka2 = ka, kb2 = kb, qa2 = qa, qb2 = qb;
;                     if (ks < 3) { ka2 = *(const LAS bf16x8*)(kp + (ks + 1) * 16); kb2 = *(const LAS bf16x8*)(kp + 64 * 72 + (ks + 1) * 16); qa2 = qsp[(ks + 1) * 64]; qb2 = qsp[(4 + ks + 1) * 64];
;                         __builtin_amdgcn_sched_group_barrier(0x100, 4, 0); }
;                     s0 = __builtin_amdgcn_mfma_f32_32x32x16_bf16(ka, qa, s0, 0, 0, 0);
;                     s1 = __builtin_amdgcn_mfma_f32_32x32x16_bf16(kb, qb, s1, 0, 0, 0);
;                     __builtin_amdgcn_sched_group_barrier(0x008, 2, 0);
;                     ka = ka2; kb = kb2; qa = qa2; qb = qb2; }
;             }
.LBB0_227:
	v_lshl_add_u64 v[128:129], v[184:185], 0, s[98:99]
	v_lshl_add_u64 v[130:131], v[182:183], 0, s[100:101]
	global_load_dwordx4 v[168:171], v[128:129], off
	global_load_dwordx4 v[172:175], v[128:129], off offset:128
	s_add_i32 s18, s58, 0xffffff50
	global_load_dwordx4 v[164:167], v[130:131], off
	global_load_dwordx4 v[160:163], v[130:131], off offset:16
	s_cmp_gt_i32 s18, s35
	s_cbranch_scc1 .LBB0_226
	s_bitcmp1_b32 s59, 0
	s_cselect_b32 s18, 0x9000, 0
	s_add_i32 s38, s18, 0
	v_add3_u32 v199, s38, v208, v192
	ds_read_b128 v[138:141], v199
	ds_read_b128 v[200:203], v199 offset:9216
	ds_read_b128 v[222:225], v199 offset:32
	ds_read_b128 v[226:229], v199 offset:9248
	v_xor_b32_e32 v144, 0x80000000, v190
	v_xor_b32_e32 v128, 0x80000000, v191
	v_mov_b32_e32 v145, v144
	v_mov_b64_e32 v[146:147], v[144:145]
	v_mov_b64_e32 v[148:149], v[144:145]
	v_mov_b64_e32 v[150:151], v[144:145]
	v_mov_b64_e32 v[152:153], v[144:145]
	v_mov_b64_e32 v[154:155], v[144:145]
	v_mov_b64_e32 v[156:157], v[144:145]
	v_mov_b64_e32 v[158:159], v[144:145]
	v_mov_b32_e32 v129, v128
	v_mov_b64_e32 v[130:131], v[128:129]
	v_mov_b64_e32 v[132:133], v[128:129]
	v_mov_b64_e32 v[134:135], v[128:129]
	v_mov_b64_e32 v[136:137], v[128:129]
	s_waitcnt lgkmcnt(3)
	v_mfma_f32_32x32x16_bf16 v[144:159], v[138:141], v[204:207], v[144:159]
	v_mov_b64_e32 v[142:143], v[128:129]
	v_mov_b64_e32 v[138:139], v[128:129]
	v_mov_b64_e32 v[140:141], v[128:129]
	s_sub_i32 s18, s58, 32
	s_cmp_le_i32 s18, s31
	s_waitcnt lgkmcnt(2)
	v_mfma_f32_32x32x16_bf16 v[128:143], v[200:203], v[218:221], v[128:143]
	ds_read_b128 v[200:203], v199 offset:64
	ds_read_b128 v[204:207], v199 offset:9280
	ds_read_b128 v[218:221], v189 offset:2048
	ds_read_b128 v[238:241], v189 offset:6144
	s_waitcnt lgkmcnt(5)
	v_mfma_f32_32x32x16_bf16 v[144:159], v[222:225], v[230:233], v[144:159]
	s_waitcnt lgkmcnt(4)
	v_mfma_f32_32x32x16_bf16 v[128:143], v[226:229], v[234:237], v[128:143]
	ds_read_b128 v[222:225], v199 offset:96
	ds_read_b128 v[226:229], v199 offset:9312
	ds_read_b128 v[230:233], v189 offset:3072
	ds_read_b128 v[234:237], v189 offset:7168
	s_waitcnt lgkmcnt(5)
	v_mfma_f32_32x32x16_bf16 v[144:159], v[200:203], v[218:221], v[144:159]
	s_cbranch_scc0 .Lqk_diag0
	s_waitcnt lgkmcnt(1)
	v_mfma_f32_32x32x16_bf16 v[144:159], v[222:225], v[230:233], v[144:159]
	v_add3_u32 v219, s38, v193, v192
	ds_read_b128 v[212:215], v219 offset:32256
	ds_read_b128 v[220:223], v219 offset:18432
	v_mfma_f32_32x32x16_bf16 v[128:143], v[204:207], v[238:241], v[128:143]
	s_waitcnt lgkmcnt(2)
	v_mfma_f32_32x32x16_bf16 v[128:143], v[226:229], v[234:237], v[128:143]
	ds_read_b128 v[228:231], v219 offset:23040
	ds_read_b128 v[232:235], v219 offset:23072
	ds_read_b128 v[236:239], v219 offset:27648
	ds_read_b128 v[240:243], v219 offset:27680
	s_nop 1

; #define LAS __attribute__((address_space(3)))
; #define AT_RAISE(MP) do { if (trig[MP]) { const float dl = fmaxf(__builtin_amdgcn_logf(pmx[MP]), 0.f), al = __builtin_amdgcn_exp2f(-dl); mref[MP] += dl; lsum[MP] *= al; \
;                 _Pragma("unroll") for (int cb = 0; cb < 4; ++cb) o[MP][cb] = o[MP][cb] * al; } } while (0)
; __device__ __forceinline__ void dattn_unit(LAS unsigned char* lds, int b, int h, int qb, const bf16* Q, const bf16* K, const bf16* V, bf16* YB, float lam, const float* subg, float oml, int tid) {
;     ...
;             for (int cb = 0; cb < 4; ++cb) { const LAS bf16* vp = Vt + (32 * cb + ql) * 72 + 32 * sub + 4 * hi;
;                 const v2u a0 = *(const LAS v2u*)(vp), a1 = *(const LAS v2u*)(vp + 8), a2 = *(const LAS v2u*)(vp + 16), a3 = *(const LAS v2u*)(vp + 24);
;                 const v4u f0 = {a0.x, a0.y, a1.x, a1.y}, f1 = {a2.x, a2.y, a3.x, a3.y};
;                 o[0][cb] = __builtin_amdgcn_mfma_f32_32x32x16_bf16(__builtin_bit_cast(bf16x8, f0), pA0, o[0][cb], 0, 0, 0);
;                 o[1][cb] = __builtin_amdgcn_mfma_f32_32x32x16_bf16(__builtin_bit_cast(bf16x8, f0), pA1, o[1][cb], 0, 0, 0);
;                 o[0][cb] = __builtin_amdgcn_mfma_f32_32x32x16_bf16(__builtin_bit_cast(bf16x8, f1), pB0, o[0][cb], 0, 0, 0);
;                 o[1][cb] = __builtin_amdgcn_mfma_f32_32x32x16_bf16(__builtin_bit_cast(bf16x8, f1), pB1, o[1][cb], 0, 0, 0); }
;             AT_RAISE(0); AT_RAISE(1);
.LBB0_245:
	v_cvt_pk_bf16_f32 v152, v155, v129
	v_cvt_pk_bf16_f32 v153, v130, v131
	v_cvt_pk_bf16_f32 v154, v132, v156
	v_cvt_pk_bf16_f32 v155, v157, v158
	v_cvt_pk_bf16_f32 v130, v133, v134
	v_cvt_pk_bf16_f32 v131, v135, v136
	v_cvt_pk_bf16_f32 v132, v137, v138
	v_cvt_pk_bf16_f32 v133, v139, v140
	s_xor_b32 s18, s38, 0x9000
	v_add3_u32 v148, s18, v196, v180
	v_add3_u32 v149, s18, v197, v195
	s_andn2_b64 vcc, exec, s[48:49]
	s_nop 0
	v_mfma_f32_32x32x16_bf16 v[64:79], v[222:225], v[152:155], v[64:79]
	s_waitcnt vmcnt(3)
	ds_write_b128 v148, v[168:171]
	ds_read_b128 v[204:207], v189
	v_mfma_f32_32x32x16_bf16 v[64:79], v[226:229], v[130:133], v[64:79]
	s_waitcnt vmcnt(2)
	ds_write_b128 v148, v[172:175] offset:9216
	v_mfma_f32_32x32x16_bf16 v[32:47], v[230:233], v[152:155], v[32:47]
	ds_read_b128 v[230:233], v189 offset:1024
	s_waitcnt vmcnt(1)
	ds_write_b16 v149, v164 offset:18432
	ds_write_b16_d16_hi v149, v164 offset:18576
	ds_write_b16 v149, v165 offset:18720
	v_mfma_f32_32x32x16_bf16 v[32:47], v[234:237], v[130:133], v[32:47]
	ds_read_b128 v[234:237], v189 offset:5120
	ds_write_b16_d16_hi v149, v165 offset:18864
	ds_write_b16 v149, v166 offset:19008
	ds_write_b16_d16_hi v149, v166 offset:19152
	v_mfma_f32_32x32x16_bf16 v[96:111], v[212:215], v[152:155], v[96:111]
	ds_write_b16 v149, v167 offset:19296
	ds_write_b16_d16_hi v149, v167 offset:19440
	s_waitcnt vmcnt(0)
	ds_write_b16 v149, v160 offset:19584
	v_mfma_f32_32x32x16_bf16 v[96:111], v[200:203], v[130:133], v[96:111]
	ds_write_b16_d16_hi v149, v160 offset:19728
	ds_write_b16 v149, v161 offset:19872
	ds_write_b16_d16_hi v149, v161 offset:20016
	v_mfma_f32_32x32x16_bf16 v[0:15], v[238:241], v[152:155], v[0:15]
	ds_write_b16 v149, v162 offset:20160
	ds_write_b16_d16_hi v149, v162 offset:20304
	v_mfma_f32_32x32x16_bf16 v[0:15], v[218:221], v[130:133], v[0:15]
	ds_read_b128 v[218:221], v189 offset:4096
	ds_write_b16 v149, v163 offset:20448
	ds_write_b16_d16_hi v149, v163 offset:20592
	s_cbranch_vccnz .LBB0_247
	v_log_f32_e32 v129, v146
	s_nop 0
	v_max_f32_e32 v129, 0, v129
	v_exp_f32_e64 v130, -v129
	v_add_f32_e32 v190, v190, v129
	s_nop 1
	v_pk_mul_f32 v[126:127], v[130:131], v[126:127] op_sel_hi:[0,1]
	v_pk_mul_f32 v[124:125], v[130:131], v[124:125] op_sel_hi:[0,1]
	v_pk_mul_f32 v[122:123], v[130:131], v[122:123] op_sel_hi:[0,1]
	v_pk_mul_f32 v[120:121], v[130:131], v[120:121] op_sel_hi:[0,1]
	v_pk_mul_f32 v[118:119], v[130:131], v[118:119] op_sel_hi:[0,1]
	v_pk_mul_f32 v[116:117], v[130:131], v[116:117] op_sel_hi:[0,1]
	v_pk_mul_f32 v[114:115], v[130:131], v[114:115] op_sel_hi:[0,1]
	v_pk_mul_f32 v[112:113], v[130:131], v[112:113] op_sel_hi:[0,1]
	v_pk_mul_f32 v[94:95], v[130:131], v[94:95] op_sel_hi:[0,1]
	v_pk_mul_f32 v[92:93], v[130:131], v[92:93] op_sel_hi:[0,1]
	v_pk_mul_f32 v[90:91], v[130:131], v[90:91] op_sel_hi:[0,1]
	v_pk_mul_f32 v[88:89], v[130:131], v[88:89] op_sel_hi:[0,1]
	v_pk_mul_f32 v[86:87], v[130:131], v[86:87] op_sel_hi:[0,1]
	v_pk_mul_f32 v[84:85], v[130:131], v[84:85] op_sel_hi:[0,1]
	v_pk_mul_f32 v[82:83], v[130:131], v[82:83] op_sel_hi:[0,1]
	v_pk_mul_f32 v[80:81], v[130:131], v[80:81] op_sel_hi:[0,1]
	v_pk_mul_f32 v[62:63], v[130:131], v[62:63] op_sel_hi:[0,1]
	v_pk_mul_f32 v[60:61], v[130:131], v[60:61] op_sel_hi:[0,1]
	v_pk_mul_f32 v[58:59], v[130:131], v[58:59] op_sel_hi:[0,1]
	v_pk_mul_f32 v[56:57], v[130:131], v[56:57] op_sel_hi:[0,1]
	v_pk_mul_f32 v[54:55], v[130:131], v[54:55] op_sel_hi:[0,1]
	v_pk_mul_f32 v[52:53], v[130:131], v[52:53] op_sel_hi:[0,1]
	v_pk_mul_f32 v[50:51], v[130:131], v[50:51] op_sel_hi:[0,1]
	v_pk_mul_f32 v[48:49], v[130:131], v[48:49] op_sel_hi:[0,1]
	v_pk_mul_f32 v[30:31], v[130:131], v[30:31] op_sel_hi:[0,1]
	v_pk_mul_f32 v[28:29], v[130:131], v[28:29] op_sel_hi:[0,1]
	v_pk_mul_f32 v[26:27], v[130:131], v[26:27] op_sel_hi:[0,1]
	v_pk_mul_f32 v[24:25], v[130:131], v[24:25] op_sel_hi:[0,1]
	v_pk_mul_f32 v[22:23], v[130:131], v[22:23] op_sel_hi:[0,1]
	v_pk_mul_f32 v[20:21], v[130:131], v[20:21] op_sel_hi:[0,1]
	v_pk_mul_f32 v[18:19], v[130:131], v[18:19] op_sel_hi:[0,1]
	v_pk_mul_f32 v[16:17], v[130:131], v[16:17] op_sel_hi:[0,1]
	v_mul_f32_e32 v179, v179, v130
